# S5 item setup: B-projection rows of all state tiles touched up front so the later per-tile loads hit the cache
# speedup vs baseline: 1.0537x; 1.0025x over previous
.LBB0_788:
	s_andn2_saveexec_b64 s[14:15], s[14:15]
	v_mul_f32_e64 v4, |v9|, s94
	v_rndne_f32_e32 v4, v4
	v_cvt_i32_f32_e32 v13, v4
	v_fma_f32 v12, v4, s95, |v9|
	v_fmac_f32_e32 v12, 0xb3a22168, v4
	v_fmac_f32_e32 v12, 0xa7c234c4, v4
	s_or_b64 exec, exec, s[14:15]
	s_or_b32 s2, s52, s9
	s_ashr_i32 s3, s2, 31
	v_mov_b32_e32 v4, 0
	s_lshl_b64 s[96:97], s[2:3], 10
	v_mov_b32_e32 v5, v4
	v_mov_b32_e32 v6, v4
	v_mov_b32_e32 v7, v4
	s_and_saveexec_b64 s[14:15], s[40:41]
	s_cbranch_execz .LBB0_792
	s_waitcnt vmcnt(0)
	v_max_f32_e32 v4, v11, v11
	v_min_f32_e32 v4, 0xb8d1b717, v4
	v_mul_f32_e32 v5, v105, v4
	v_mul_f32_e32 v6, 0x3fb8aa3b, v5
	v_fma_f32 v7, v5, s27, -v6
	v_rndne_f32_e32 v11, v6
	v_fmac_f32_e32 v7, 0x32a5705f, v5
	v_sub_f32_e32 v6, v6, v11
	v_add_f32_e32 v6, v6, v7
	v_exp_f32_e32 v6, v6
	v_cvt_i32_f32_e32 v7, v11
	v_cmp_ngt_f32_e32 vcc, s29, v5
	v_ldexp_f32 v6, v6, v7
	v_and_b32_e32 v7, 1, v13
	v_cndmask_b32_e32 v6, 0, v6, vcc
	v_cmp_nlt_f32_e32 vcc, s10, v5
	v_cmp_eq_u32_e64 s[46:47], 0, v7
	v_mul_f32_e32 v7, v12, v12
	v_cndmask_b32_e32 v5, v223, v6, vcc
	v_cmp_class_f32_e64 vcc, v9, s28
	v_xor_b32_e32 v6, v10, v9
	v_fmamk_f32 v9, v7, 0xb94c1982, v219
	v_fmaak_f32 v9, v7, v9, 0xbe2aaa9d
	v_mul_f32_e32 v9, v7, v9
	v_fmac_f32_e32 v12, v12, v9
	v_fmamk_f32 v9, v7, 0x37d75334, v220
	v_fmaak_f32 v9, v7, v9, 0x3d2aabf7
	v_fmaak_f32 v9, v7, v9, 0xbf000004
	v_fma_f32 v7, v7, v9, 1.0
	v_cndmask_b32_e64 v9, v7, v12, s[46:47]
	v_lshlrev_b32_e32 v10, 30, v13
	v_xor_b32_e32 v6, v6, v9
	v_xor_b32_e32 v9, 0x80000000, v12
	v_and_b32_e32 v11, 0x80000000, v10
	v_cndmask_b32_e64 v7, v9, v7, s[46:47]
	v_xor_b32_e32 v6, v6, v11
	v_bitop3_b32 v7, v7, v10, s33 bitop3:0x78
	v_cndmask_b32_e32 v6, v251, v6, vcc
	v_cndmask_b32_e32 v7, v251, v7, vcc
	v_mul_f32_e32 v6, v5, v6
	v_fma_f32 v10, v5, v7, -1.0
	v_mov_b32_e32 v7, v4
	v_mov_b32_e32 v11, v8
	v_pk_mul_f32 v[12:13], v[4:5], v[6:7] op_sel_hi:[0,1]
	v_pk_mul_f32 v[14:15], v[8:9], v[10:11] op_sel_hi:[0,1]
	v_sub_f32_e32 v5, v12, v14
	v_add_f32_e32 v7, v13, v15
	v_div_scale_f32 v9, s[2:3], v7, v7, v5
	v_rcp_f32_e32 v11, v9
	s_nop 0
	v_fma_f32 v12, -v9, v11, 1.0
	v_fmac_f32_e32 v11, v12, v11
	v_div_scale_f32 v12, vcc, v5, v7, v5
	v_mul_f32_e32 v13, v12, v11
	v_fma_f32 v14, -v9, v13, v12
	v_fmac_f32_e32 v13, v14, v11
	v_fma_f32 v9, -v9, v13, v12
	v_div_fmas_f32 v9, v9, v11, v13
	v_div_fixup_f32 v20, v9, v7, v5
	v_mov_b32_e32 v5, v8
	v_mov_b32_e32 v11, v6
	v_pk_mul_f32 v[4:5], v[4:5], v[10:11]
	s_nop 0
	v_add_f32_e32 v4, v4, v5
	v_div_scale_f32 v5, s[2:3], v7, v7, v4
	v_rcp_f32_e32 v6, v5
	s_nop 0
	v_fma_f32 v8, -v5, v6, 1.0
	v_fmac_f32_e32 v6, v8, v6
	v_div_scale_f32 v8, vcc, v4, v7, v4
	v_mul_f32_e32 v9, v8, v6
	v_fma_f32 v10, -v5, v9, v8
	v_fmac_f32_e32 v9, v10, v6
	v_fma_f32 v5, -v5, v9, v8
	v_div_fmas_f32 v5, v5, v6, v9
	v_div_fixup_f32 v22, v5, v7, v4
	v_mov_b32_e32 v5, s97
	v_or_b32_e32 v4, s96, v92
	v_lshlrev_b64 v[4:5], 2, v[4:5]
	v_lshl_add_u64 v[8:9], v[112:113], 0, v[4:5]
	v_lshl_add_u64 v[16:17], v[114:115], 0, v[4:5]
	global_load_dwordx4 v[208:211], v[8:9], off offset:528
	global_load_dwordx4 v[208:211], v[8:9], off offset:512
	global_load_dwordx4 v[208:211], v[16:17], off offset:528
	global_load_dwordx4 v[208:211], v[16:17], off offset:512
	global_load_dwordx4 v[208:211], v[8:9], off offset:1040
	global_load_dwordx4 v[208:211], v[8:9], off offset:1024
	global_load_dwordx4 v[208:211], v[16:17], off offset:1040
	global_load_dwordx4 v[208:211], v[16:17], off offset:1024
	global_load_dwordx4 v[208:211], v[8:9], off offset:1552
	global_load_dwordx4 v[208:211], v[8:9], off offset:1536
	global_load_dwordx4 v[208:211], v[16:17], off offset:1552
	global_load_dwordx4 v[208:211], v[16:17], off offset:1536
	global_load_dwordx4 v[208:211], v[8:9], off offset:2064
	global_load_dwordx4 v[208:211], v[8:9], off offset:2048
	global_load_dwordx4 v[208:211], v[16:17], off offset:2064
	global_load_dwordx4 v[208:211], v[16:17], off offset:2048
	global_load_dwordx4 v[208:211], v[8:9], off offset:2576
	global_load_dwordx4 v[208:211], v[8:9], off offset:2560
	global_load_dwordx4 v[208:211], v[16:17], off offset:2576
	global_load_dwordx4 v[208:211], v[16:17], off offset:2560
	global_load_dwordx4 v[208:211], v[8:9], off offset:3088
	global_load_dwordx4 v[208:211], v[8:9], off offset:3072
	global_load_dwordx4 v[208:211], v[16:17], off offset:3088
	global_load_dwordx4 v[208:211], v[16:17], off offset:3072
	global_load_dwordx4 v[208:211], v[8:9], off offset:3600
	global_load_dwordx4 v[208:211], v[8:9], off offset:3584
	global_load_dwordx4 v[208:211], v[16:17], off offset:3600
	global_load_dwordx4 v[208:211], v[16:17], off offset:3584
	global_load_dwordx4 v[4:7], v[8:9], off offset:16
	global_load_dwordx4 v[12:15], v[8:9], off
	s_nop 0
	global_load_dwordx4 v[8:11], v[16:17], off offset:16
	s_nop 0
	global_load_dwordx4 v[16:19], v[16:17], off
	s_waitcnt vmcnt(0)
	v_pk_mul_f32 v[24:25], v[22:23], v[18:19] op_sel_hi:[0,1]
	v_pk_mul_f32 v[26:27], v[22:23], v[16:17] op_sel_hi:[0,1]
	v_pk_mul_f32 v[18:19], v[20:21], v[18:19] op_sel_hi:[0,1]
	v_pk_mul_f32 v[16:17], v[20:21], v[16:17] op_sel_hi:[0,1]
	v_pk_fma_f32 v[26:27], v[20:21], v[12:13], v[26:27] op_sel_hi:[0,1,1]
	v_pk_fma_f32 v[24:25], v[20:21], v[14:15], v[24:25] op_sel_hi:[0,1,1]
	v_pk_fma_f32 v[12:13], v[22:23], v[12:13], v[16:17] op_sel_hi:[0,1,1] neg_lo:[0,0,1] neg_hi:[0,0,1]
	v_pk_fma_f32 v[14:15], v[22:23], v[14:15], v[18:19] op_sel_hi:[0,1,1] neg_lo:[0,0,1] neg_hi:[0,0,1]
	v_cndmask_b32_e64 v16, v25, v15, s[44:45]
	v_cndmask_b32_e64 v17, v24, v14, s[44:45]
	v_cndmask_b32_e64 v18, v27, v13, s[44:45]
	v_cndmask_b32_e64 v19, v26, v12, s[44:45]
	v_pk_mul_f32 v[12:13], v[22:23], v[10:11] op_sel_hi:[0,1]
	v_pk_mul_f32 v[14:15], v[22:23], v[8:9] op_sel_hi:[0,1]
	v_pk_mul_f32 v[10:11], v[20:21], v[10:11] op_sel_hi:[0,1]
	v_pk_mul_f32 v[8:9], v[20:21], v[8:9] op_sel_hi:[0,1]
	v_pk_fma_f32 v[14:15], v[20:21], v[4:5], v[14:15] op_sel_hi:[0,1,1]
	v_pk_fma_f32 v[12:13], v[20:21], v[6:7], v[12:13] op_sel_hi:[0,1,1]
	v_pk_fma_f32 v[4:5], v[22:23], v[4:5], v[8:9] op_sel_hi:[0,1,1] neg_lo:[0,0,1] neg_hi:[0,0,1]
	v_pk_fma_f32 v[6:7], v[22:23], v[6:7], v[10:11] op_sel_hi:[0,1,1] neg_lo:[0,0,1] neg_hi:[0,0,1]
	v_cndmask_b32_e64 v7, v13, v7, s[44:45]
	v_cndmask_b32_e64 v8, v12, v6, s[44:45]
	v_cndmask_b32_e64 v6, v15, v5, s[44:45]
	v_cndmask_b32_e64 v9, v14, v4, s[44:45]
	v_cvt_pk_bf16_f32 v4, v19, v18
	v_cvt_pk_bf16_f32 v5, v17, v16
	v_cvt_pk_bf16_f32 v6, v9, v6
	v_cvt_pk_bf16_f32 v7, v8, v7

.LBB0_857:
	s_andn2_saveexec_b64 s[14:15], s[14:15]
	v_mul_f32_e64 v4, |v9|, s94
	v_rndne_f32_e32 v4, v4
	v_cvt_i32_f32_e32 v13, v4
	v_fma_f32 v12, v4, s95, |v9|
	v_fmac_f32_e32 v12, 0xb3a22168, v4
	v_fmac_f32_e32 v12, 0xa7c234c4, v4
	s_or_b64 exec, exec, s[14:15]
	s_or_b32 s2, s7, s9
	s_ashr_i32 s3, s2, 31
	v_mov_b32_e32 v4, 0
	s_lshl_b64 s[58:59], s[2:3], 10
	v_mov_b32_e32 v5, v4
	v_mov_b32_e32 v6, v4
	v_mov_b32_e32 v7, v4
	s_and_saveexec_b64 s[14:15], s[40:41]
	s_cbranch_execz .LBB0_861
	s_waitcnt vmcnt(0)
	v_max_f32_e32 v4, v11, v11
	v_min_f32_e32 v4, 0xb8d1b717, v4
	v_mul_f32_e32 v5, v103, v4
	v_mul_f32_e32 v6, 0x3fb8aa3b, v5
	v_fma_f32 v7, v5, s27, -v6
	v_rndne_f32_e32 v11, v6
	v_fmac_f32_e32 v7, 0x32a5705f, v5
	v_sub_f32_e32 v6, v6, v11
	v_add_f32_e32 v6, v6, v7
	v_exp_f32_e32 v6, v6
	v_cvt_i32_f32_e32 v7, v11
	v_cmp_ngt_f32_e32 vcc, s29, v5
	v_ldexp_f32 v6, v6, v7
	v_and_b32_e32 v7, 1, v13
	v_cndmask_b32_e32 v6, 0, v6, vcc
	v_cmp_nlt_f32_e32 vcc, s10, v5
	v_cmp_eq_u32_e64 s[46:47], 0, v7
	v_mul_f32_e32 v7, v12, v12
	v_cndmask_b32_e32 v5, v223, v6, vcc
	v_cmp_class_f32_e64 vcc, v9, s28
	v_xor_b32_e32 v6, v10, v9
	v_fmamk_f32 v9, v7, 0xb94c1982, v219
	v_fmaak_f32 v9, v7, v9, 0xbe2aaa9d
	v_mul_f32_e32 v9, v7, v9
	v_fmac_f32_e32 v12, v12, v9
	v_fmamk_f32 v9, v7, 0x37d75334, v220
	v_fmaak_f32 v9, v7, v9, 0x3d2aabf7
	v_fmaak_f32 v9, v7, v9, 0xbf000004
	v_fma_f32 v7, v7, v9, 1.0
	v_cndmask_b32_e64 v9, v7, v12, s[46:47]
	v_lshlrev_b32_e32 v10, 30, v13
	v_xor_b32_e32 v6, v6, v9
	v_xor_b32_e32 v9, 0x80000000, v12
	v_and_b32_e32 v11, 0x80000000, v10
	v_cndmask_b32_e64 v7, v9, v7, s[46:47]
	v_xor_b32_e32 v6, v6, v11
	v_bitop3_b32 v7, v7, v10, s33 bitop3:0x78
	v_cndmask_b32_e32 v6, v251, v6, vcc
	v_cndmask_b32_e32 v7, v251, v7, vcc
	v_mul_f32_e32 v6, v5, v6
	v_fma_f32 v10, v5, v7, -1.0
	v_mov_b32_e32 v7, v4
	v_mov_b32_e32 v11, v8
	v_pk_mul_f32 v[12:13], v[4:5], v[6:7] op_sel_hi:[0,1]
	v_pk_mul_f32 v[14:15], v[8:9], v[10:11] op_sel_hi:[0,1]
	v_sub_f32_e32 v5, v12, v14
	v_add_f32_e32 v7, v13, v15
	v_div_scale_f32 v9, s[2:3], v7, v7, v5
	v_rcp_f32_e32 v11, v9
	s_nop 0
	v_fma_f32 v12, -v9, v11, 1.0
	v_fmac_f32_e32 v11, v12, v11
	v_div_scale_f32 v12, vcc, v5, v7, v5
	v_mul_f32_e32 v13, v12, v11
	v_fma_f32 v14, -v9, v13, v12
	v_fmac_f32_e32 v13, v14, v11
	v_fma_f32 v9, -v9, v13, v12
	v_div_fmas_f32 v9, v9, v11, v13
	v_div_fixup_f32 v20, v9, v7, v5
	v_mov_b32_e32 v5, v8
	v_mov_b32_e32 v11, v6
	v_pk_mul_f32 v[4:5], v[4:5], v[10:11]
	s_nop 0
	v_add_f32_e32 v4, v4, v5
	v_div_scale_f32 v5, s[2:3], v7, v7, v4
	v_rcp_f32_e32 v6, v5
	s_nop 0
	v_fma_f32 v8, -v5, v6, 1.0
	v_fmac_f32_e32 v6, v8, v6
	v_div_scale_f32 v8, vcc, v4, v7, v4
	v_mul_f32_e32 v9, v8, v6
	v_fma_f32 v10, -v5, v9, v8
	v_fmac_f32_e32 v9, v10, v6
	v_fma_f32 v5, -v5, v9, v8
	v_div_fmas_f32 v5, v5, v6, v9
	v_div_fixup_f32 v22, v5, v7, v4
	v_mov_b32_e32 v5, s59
	v_or_b32_e32 v4, s58, v92
	v_lshlrev_b64 v[4:5], 2, v[4:5]
	v_lshl_add_u64 v[8:9], v[112:113], 0, v[4:5]
	v_lshl_add_u64 v[16:17], v[114:115], 0, v[4:5]
	global_load_dwordx4 v[208:211], v[8:9], off offset:528
	global_load_dwordx4 v[208:211], v[8:9], off offset:512
	global_load_dwordx4 v[208:211], v[16:17], off offset:528
	global_load_dwordx4 v[208:211], v[16:17], off offset:512
	global_load_dwordx4 v[208:211], v[8:9], off offset:1040
	global_load_dwordx4 v[208:211], v[8:9], off offset:1024
	global_load_dwordx4 v[208:211], v[16:17], off offset:1040
	global_load_dwordx4 v[208:211], v[16:17], off offset:1024
	global_load_dwordx4 v[208:211], v[8:9], off offset:1552
	global_load_dwordx4 v[208:211], v[8:9], off offset:1536
	global_load_dwordx4 v[208:211], v[16:17], off offset:1552
	global_load_dwordx4 v[208:211], v[16:17], off offset:1536
	global_load_dwordx4 v[208:211], v[8:9], off offset:2064
	global_load_dwordx4 v[208:211], v[8:9], off offset:2048
	global_load_dwordx4 v[208:211], v[16:17], off offset:2064
	global_load_dwordx4 v[208:211], v[16:17], off offset:2048
	global_load_dwordx4 v[208:211], v[8:9], off offset:2576
	global_load_dwordx4 v[208:211], v[8:9], off offset:2560
	global_load_dwordx4 v[208:211], v[16:17], off offset:2576
	global_load_dwordx4 v[208:211], v[16:17], off offset:2560
	global_load_dwordx4 v[208:211], v[8:9], off offset:3088
	global_load_dwordx4 v[208:211], v[8:9], off offset:3072
	global_load_dwordx4 v[208:211], v[16:17], off offset:3088
	global_load_dwordx4 v[208:211], v[16:17], off offset:3072
	global_load_dwordx4 v[208:211], v[8:9], off offset:3600
	global_load_dwordx4 v[208:211], v[8:9], off offset:3584
	global_load_dwordx4 v[208:211], v[16:17], off offset:3600
	global_load_dwordx4 v[208:211], v[16:17], off offset:3584
	global_load_dwordx4 v[4:7], v[8:9], off offset:16
	global_load_dwordx4 v[12:15], v[8:9], off
	s_nop 0
	global_load_dwordx4 v[8:11], v[16:17], off offset:16
	s_nop 0
	global_load_dwordx4 v[16:19], v[16:17], off
	s_waitcnt vmcnt(0)
	v_pk_mul_f32 v[24:25], v[22:23], v[18:19] op_sel_hi:[0,1]
	v_pk_mul_f32 v[26:27], v[22:23], v[16:17] op_sel_hi:[0,1]
	v_pk_mul_f32 v[18:19], v[20:21], v[18:19] op_sel_hi:[0,1]
	v_pk_mul_f32 v[16:17], v[20:21], v[16:17] op_sel_hi:[0,1]
	v_pk_fma_f32 v[26:27], v[20:21], v[12:13], v[26:27] op_sel_hi:[0,1,1]
	v_pk_fma_f32 v[24:25], v[20:21], v[14:15], v[24:25] op_sel_hi:[0,1,1]
	v_pk_fma_f32 v[12:13], v[22:23], v[12:13], v[16:17] op_sel_hi:[0,1,1] neg_lo:[0,0,1] neg_hi:[0,0,1]
	v_pk_fma_f32 v[14:15], v[22:23], v[14:15], v[18:19] op_sel_hi:[0,1,1] neg_lo:[0,0,1] neg_hi:[0,0,1]
	v_cndmask_b32_e64 v16, v25, v15, s[44:45]
	v_cndmask_b32_e64 v17, v24, v14, s[44:45]
	v_cndmask_b32_e64 v18, v27, v13, s[44:45]
	v_cndmask_b32_e64 v19, v26, v12, s[44:45]
	v_pk_mul_f32 v[12:13], v[22:23], v[10:11] op_sel_hi:[0,1]
	v_pk_mul_f32 v[14:15], v[22:23], v[8:9] op_sel_hi:[0,1]
	v_pk_mul_f32 v[10:11], v[20:21], v[10:11] op_sel_hi:[0,1]
	v_pk_mul_f32 v[8:9], v[20:21], v[8:9] op_sel_hi:[0,1]
	v_pk_fma_f32 v[14:15], v[20:21], v[4:5], v[14:15] op_sel_hi:[0,1,1]
	v_pk_fma_f32 v[12:13], v[20:21], v[6:7], v[12:13] op_sel_hi:[0,1,1]
	v_pk_fma_f32 v[4:5], v[22:23], v[4:5], v[8:9] op_sel_hi:[0,1,1] neg_lo:[0,0,1] neg_hi:[0,0,1]
	v_pk_fma_f32 v[6:7], v[22:23], v[6:7], v[10:11] op_sel_hi:[0,1,1] neg_lo:[0,0,1] neg_hi:[0,0,1]
	v_cndmask_b32_e64 v7, v13, v7, s[44:45]
	v_cndmask_b32_e64 v8, v12, v6, s[44:45]
	v_cndmask_b32_e64 v6, v15, v5, s[44:45]
	v_cndmask_b32_e64 v9, v14, v4, s[44:45]
	v_cvt_pk_bf16_f32 v4, v19, v18
	v_cvt_pk_bf16_f32 v5, v17, v16
	v_cvt_pk_bf16_f32 v6, v9, v6
	v_cvt_pk_bf16_f32 v7, v8, v7
